# v12: scan RET: all 8 chunk loads of a thread-item issued up front, constant counted vmcnt(7) instead of per-chunk vmcnt(0)
# speedup vs baseline: 1.0809x; 1.0050x over previous
; __device__ __forceinline__ unsigned pk2(float lo, float hi) { return pg8::cvt_pk_bf16(lo, hi); }
; template <int DK, int DV, int NC, bool RET> __device__ __forceinline__ void scan_states(const bf16_t* HL, const float* DEC, bf16_t* ST, float* outp) {
;     ...
;         f32x4 S = (f32x4){0.f, 0.f, 0.f, 0.f}; float c_st = 1.f, c_dec = 1.f, c_h = 1.f;
;         if (RET) { const float l2g = __log2f(1.0f - exp2f(-5.0f - (float)(bh & 3))); c_st = exp2f(129.f * l2g); c_dec = exp2f(256.f * l2g); c_h = exp2f(127.f * l2g); }
; #pragma unroll 8
;         for (int c = 0; c < NC; ++c) { const size_t base = (((size_t)bh * NC + c) * DV + e) * DK + dq * 4;
;             if (c != 0) { u32x2 w; w.x = pk2(S[0] * c_st, S[1] * c_st); w.y = pk2(S[2] * c_st, S[3] * c_st); *(u32x2*)(ST + base) = w; }
;             const u32x2 hw = __builtin_nontemporal_load((const u32x2*)(HL + base)); const f32x4 hl = (f32x4){bf2f(hw.x & 0xffffu), bf2f(hw.x >> 16), bf2f(hw.y & 0xffffu), bf2f(hw.y >> 16)};
;             f32x4 dec; if (RET) dec = (f32x4){c_dec, c_dec, c_dec, c_dec}; else dec = *(const f32x4*)(DEC + ((size_t)bh * NC + c) * DK + dq * 4);
;             S = dec * S + hl * c_h; }
.LBB0_797:
	v_and_b32_e32 v1, 3, v2
	v_cvt_f32_ubyte0_e32 v1, v1
	v_sub_f32_e32 v1, 0xc0a00000, v1
	s_mov_b32 s10, 0xc2fc0000
	v_cmp_gt_f32_e32 vcc, s10, v1
	v_mov_b32_e32 v6, 0x42800000
	v_not_b32_e32 v8, 63
	v_cndmask_b32_e32 v3, 0, v6, vcc
	v_add_f32_e32 v1, v1, v3
	v_exp_f32_e32 v1, v1
	v_cndmask_b32_e32 v3, 0, v8, vcc
	v_readlane_b32 s12, v253, 34
	v_readlane_b32 s13, v253, 35
	v_ldexp_f32 v1, v1, v3
	v_sub_f32_e32 v1, 1.0, v1
	v_log_f32_e32 v1, v1
	v_readlane_b32 s14, v254, 9
	v_readlane_b32 s15, v254, 10
	v_mov_b32_e32 v19, 0
	v_mul_f32_e32 v3, 0x43010000, v1
	v_cmp_gt_f32_e32 vcc, s10, v3
	s_nop 1
	v_cndmask_b32_e32 v3, 0, v6, vcc
	v_fmac_f32_e32 v3, 0x43010000, v1
	v_exp_f32_e32 v3, v3
	v_cndmask_b32_e32 v4, 0, v8, vcc
	v_ldexp_f32 v20, v3, v4
	v_mul_f32_e32 v3, 0x43800000, v1
	v_cmp_gt_f32_e32 vcc, s10, v3
	s_nop 1
	v_cndmask_b32_e32 v3, 0, v6, vcc
	v_fmac_f32_e32 v3, 0x43800000, v1
	v_exp_f32_e32 v3, v3
	v_cndmask_b32_e32 v4, 0, v8, vcc
	v_ldexp_f32 v4, v3, v4
	v_mul_f32_e32 v3, 0x42fe0000, v1
	v_cmp_gt_f32_e32 vcc, s10, v3
	s_mov_b64 s[10:11], 0x80000
	s_nop 0
	v_cndmask_b32_e32 v3, 0, v6, vcc
	v_fmac_f32_e32 v3, 0x42fe0000, v1
	v_exp_f32_e32 v1, v3
	v_cndmask_b32_e32 v3, 0, v8, vcc
	v_ldexp_f32 v6, v1, v3
	v_ashrrev_i32_e32 v3, 31, v2
	v_lshlrev_b64 v[8:9], 12, v[2:3]
	v_ashrrev_i32_e32 v1, 31, v0
	v_lshl_add_u64 v[10:11], v[8:9], 0, v[0:1]
	v_lshlrev_b32_e32 v8, 2, v18
	v_lshlrev_b64 v[12:13], 9, v[10:11]
	v_ashrrev_i32_e32 v9, 31, v8
	v_lshl_add_u64 v[12:13], s[12:13], 0, v[12:13]
	v_lshl_add_u64 v[12:13], v[8:9], 1, v[12:13]
	v_lshlrev_b64 v[10:11], 8, v[10:11]
	v_lshl_add_u64 v[10:11], v[10:11], 0, v[8:9]
	v_lshlrev_b64 v[10:11], 1, v[10:11]
	v_lshl_add_u64 v[210:211], s[12:13], 0, v[10:11]
	s_mov_b64 s[98:99], 0x40000
	global_load_dwordx2 v[212:213], v[210:211], off
	v_lshl_add_u64 v[210:211], v[210:211], 0, s[98:99]
	global_load_dwordx2 v[214:215], v[210:211], off nt
	v_lshl_add_u64 v[210:211], v[210:211], 0, s[98:99]
	global_load_dwordx2 v[216:217], v[210:211], off nt
	v_lshl_add_u64 v[210:211], v[210:211], 0, s[98:99]
	global_load_dwordx2 v[218:219], v[210:211], off nt
	v_lshl_add_u64 v[210:211], v[210:211], 0, s[98:99]
	global_load_dwordx2 v[220:221], v[210:211], off nt
	v_lshl_add_u64 v[210:211], v[210:211], 0, s[98:99]
	global_load_dwordx2 v[222:223], v[210:211], off nt
	v_lshl_add_u64 v[210:211], v[210:211], 0, s[98:99]
	global_load_dwordx2 v[224:225], v[210:211], off nt
	v_lshl_add_u64 v[210:211], v[210:211], 0, s[98:99]
	global_load_dwordx2 v[226:227], v[210:211], off nt
	v_lshl_add_u64 v[24:25], v[10:11], 0, s[24:25]
	v_lshl_add_u64 v[26:27], s[14:15], 0, v[24:25]
	v_lshlrev_b64 v[8:9], 11, v[8:9]
	s_waitcnt vmcnt(7)
	v_lshlrev_b32_e32 v14, 16, v212
	v_and_b32_e32 v15, 0xffff0000, v212
	v_lshlrev_b32_e32 v12, 16, v213
	v_and_b32_e32 v13, 0xffff0000, v213
	v_pk_mul_f32 v[14:15], v[6:7], v[14:15] op_sel_hi:[0,1]
	v_pk_mul_f32 v[12:13], v[6:7], v[12:13] op_sel_hi:[0,1]
	v_pk_fma_f32 v[12:13], v[4:5], 0, v[12:13] op_sel_hi:[0,0,1]
	v_pk_fma_f32 v[14:15], v[4:5], 0, v[14:15] op_sel_hi:[0,0,1]
	v_mul_f32_e32 v21, v20, v14
	v_mul_f32_e32 v22, v20, v15
	v_mul_f32_e32 v23, v20, v13
	v_cvt_pk_bf16_f32 v22, v21, v22
	v_mul_f32_e32 v21, v20, v12
	v_cvt_pk_bf16_f32 v23, v21, v23
	global_store_dwordx2 v[26:27], v[22:23], off
	v_lshl_add_u64 v[22:23], s[12:13], 0, v[24:25]
	s_waitcnt vmcnt(7)
	v_lshlrev_b32_e32 v24, 16, v214
	v_and_b32_e32 v25, 0xffff0000, v214
	v_lshlrev_b32_e32 v22, 16, v215
	v_and_b32_e32 v23, 0xffff0000, v215
	v_pk_mul_f32 v[24:25], v[6:7], v[24:25] op_sel_hi:[0,1]
	v_pk_mul_f32 v[22:23], v[6:7], v[22:23] op_sel_hi:[0,1]
	v_pk_fma_f32 v[12:13], v[4:5], v[12:13], v[22:23] op_sel_hi:[0,1,1]
	v_pk_fma_f32 v[14:15], v[4:5], v[14:15], v[24:25] op_sel_hi:[0,1,1]
	v_mul_f32_e32 v21, v20, v14
	v_mul_f32_e32 v22, v20, v15
	v_mul_f32_e32 v23, v20, v13
	v_lshl_add_u64 v[24:25], v[10:11], 0, s[10:11]
	v_cvt_pk_bf16_f32 v22, v21, v22
	v_mul_f32_e32 v21, v20, v12
	v_cvt_pk_bf16_f32 v23, v21, v23
	v_lshl_add_u64 v[26:27], s[14:15], 0, v[24:25]
	global_store_dwordx2 v[26:27], v[22:23], off
	v_lshl_add_u64 v[22:23], s[12:13], 0, v[24:25]
	s_mov_b64 s[10:11], 0xc0000
	s_waitcnt vmcnt(7)
; __device__ __forceinline__ unsigned pk2(float lo, float hi) { return pg8::cvt_pk_bf16(lo, hi); }
; template <int DK, int DV, int NC, bool RET> __device__ __forceinline__ void scan_states(const bf16_t* HL, const float* DEC, bf16_t* ST, float* outp) {
;     ...
; #pragma unroll 8
;         for (int c = 0; c < NC; ++c) { const size_t base = (((size_t)bh * NC + c) * DV + e) * DK + dq * 4;
;             if (c != 0) { u32x2 w; w.x = pk2(S[0] * c_st, S[1] * c_st); w.y = pk2(S[2] * c_st, S[3] * c_st); *(u32x2*)(ST + base) = w; }
;             const u32x2 hw = __builtin_nontemporal_load((const u32x2*)(HL + base)); const f32x4 hl = (f32x4){bf2f(hw.x & 0xffffu), bf2f(hw.x >> 16), bf2f(hw.y & 0xffffu), bf2f(hw.y >> 16)};
;             f32x4 dec; if (RET) dec = (f32x4){c_dec, c_dec, c_dec, c_dec}; else dec = *(const f32x4*)(DEC + ((size_t)bh * NC + c) * DK + dq * 4);
;             S = dec * S + hl * c_h; }
; #pragma unroll
;         for (int j = 0; j < 4; ++j) outp[((size_t)bh * DK + dq * 4 + j) * DV + e] = S[j];
	v_lshlrev_b32_e32 v24, 16, v216
	v_and_b32_e32 v25, 0xffff0000, v216
	v_lshlrev_b32_e32 v22, 16, v217
	v_and_b32_e32 v23, 0xffff0000, v217
	v_pk_mul_f32 v[24:25], v[6:7], v[24:25] op_sel_hi:[0,1]
	v_pk_mul_f32 v[22:23], v[6:7], v[22:23] op_sel_hi:[0,1]
	v_pk_fma_f32 v[12:13], v[4:5], v[12:13], v[22:23] op_sel_hi:[0,1,1]
	v_pk_fma_f32 v[14:15], v[4:5], v[14:15], v[24:25] op_sel_hi:[0,1,1]
	v_mul_f32_e32 v21, v20, v14
	v_mul_f32_e32 v22, v20, v15
	v_mul_f32_e32 v23, v20, v13
	v_lshl_add_u64 v[24:25], v[10:11], 0, s[10:11]
	v_cvt_pk_bf16_f32 v22, v21, v22
	v_mul_f32_e32 v21, v20, v12
	v_cvt_pk_bf16_f32 v23, v21, v23
	v_lshl_add_u64 v[26:27], s[14:15], 0, v[24:25]
	global_store_dwordx2 v[26:27], v[22:23], off
	v_lshl_add_u64 v[22:23], s[12:13], 0, v[24:25]
	s_mov_b64 s[10:11], 0x100000
	s_waitcnt vmcnt(7)
	v_lshlrev_b32_e32 v24, 16, v218
	v_and_b32_e32 v25, 0xffff0000, v218
	v_lshlrev_b32_e32 v22, 16, v219
	v_and_b32_e32 v23, 0xffff0000, v219
	v_pk_mul_f32 v[24:25], v[6:7], v[24:25] op_sel_hi:[0,1]
	v_pk_mul_f32 v[22:23], v[6:7], v[22:23] op_sel_hi:[0,1]
	v_pk_fma_f32 v[12:13], v[4:5], v[12:13], v[22:23] op_sel_hi:[0,1,1]
	v_pk_fma_f32 v[14:15], v[4:5], v[14:15], v[24:25] op_sel_hi:[0,1,1]
	v_mul_f32_e32 v21, v20, v14
	v_mul_f32_e32 v22, v20, v15
	v_mul_f32_e32 v23, v20, v13
	v_lshl_add_u64 v[24:25], v[10:11], 0, s[10:11]
	v_cvt_pk_bf16_f32 v22, v21, v22
	v_mul_f32_e32 v21, v20, v12
	v_cvt_pk_bf16_f32 v23, v21, v23
	v_lshl_add_u64 v[26:27], s[14:15], 0, v[24:25]
	global_store_dwordx2 v[26:27], v[22:23], off
	v_lshl_add_u64 v[22:23], s[12:13], 0, v[24:25]
	s_mov_b64 s[10:11], 0x140000
	s_waitcnt vmcnt(7)
	v_lshlrev_b32_e32 v24, 16, v220
	v_and_b32_e32 v25, 0xffff0000, v220
	v_lshlrev_b32_e32 v22, 16, v221
	v_and_b32_e32 v23, 0xffff0000, v221
	v_pk_mul_f32 v[24:25], v[6:7], v[24:25] op_sel_hi:[0,1]
	v_pk_mul_f32 v[22:23], v[6:7], v[22:23] op_sel_hi:[0,1]
	v_pk_fma_f32 v[12:13], v[4:5], v[12:13], v[22:23] op_sel_hi:[0,1,1]
	v_pk_fma_f32 v[14:15], v[4:5], v[14:15], v[24:25] op_sel_hi:[0,1,1]
	v_mul_f32_e32 v21, v20, v14
	v_mul_f32_e32 v22, v20, v15
	v_mul_f32_e32 v23, v20, v13
	v_lshl_add_u64 v[24:25], v[10:11], 0, s[10:11]
	v_cvt_pk_bf16_f32 v22, v21, v22
	v_mul_f32_e32 v21, v20, v12
	v_cvt_pk_bf16_f32 v23, v21, v23
	v_lshl_add_u64 v[26:27], s[14:15], 0, v[24:25]
	global_store_dwordx2 v[26:27], v[22:23], off
	v_lshl_add_u64 v[22:23], s[12:13], 0, v[24:25]
	s_mov_b64 s[10:11], 0x180000
	s_waitcnt vmcnt(7)
	v_lshlrev_b32_e32 v24, 16, v222
	v_and_b32_e32 v25, 0xffff0000, v222
	v_lshlrev_b32_e32 v22, 16, v223
	v_and_b32_e32 v23, 0xffff0000, v223
	v_pk_mul_f32 v[24:25], v[6:7], v[24:25] op_sel_hi:[0,1]
	v_pk_mul_f32 v[22:23], v[6:7], v[22:23] op_sel_hi:[0,1]
	v_pk_fma_f32 v[12:13], v[4:5], v[12:13], v[22:23] op_sel_hi:[0,1,1]
	v_pk_fma_f32 v[14:15], v[4:5], v[14:15], v[24:25] op_sel_hi:[0,1,1]
	v_mul_f32_e32 v21, v20, v14
	v_mul_f32_e32 v22, v20, v15
	v_mul_f32_e32 v23, v20, v13
	v_lshl_add_u64 v[24:25], v[10:11], 0, s[10:11]
	v_cvt_pk_bf16_f32 v22, v21, v22
	v_mul_f32_e32 v21, v20, v12
	v_cvt_pk_bf16_f32 v23, v21, v23
	v_lshl_add_u64 v[26:27], s[14:15], 0, v[24:25]
	global_store_dwordx2 v[26:27], v[22:23], off
	v_lshl_add_u64 v[22:23], s[12:13], 0, v[24:25]
	s_mov_b64 s[10:11], 0x1c0000
	v_lshl_add_u64 v[10:11], v[10:11], 0, s[10:11]
	v_readlane_b32 s10, v253, 38
	v_readlane_b32 s11, v253, 39
	s_waitcnt vmcnt(7)
	v_lshlrev_b32_e32 v24, 16, v224
	v_and_b32_e32 v25, 0xffff0000, v224
	v_lshlrev_b32_e32 v22, 16, v225
	v_and_b32_e32 v23, 0xffff0000, v225
	v_pk_mul_f32 v[24:25], v[6:7], v[24:25] op_sel_hi:[0,1]
	v_pk_mul_f32 v[22:23], v[6:7], v[22:23] op_sel_hi:[0,1]
	v_pk_fma_f32 v[14:15], v[4:5], v[14:15], v[24:25] op_sel_hi:[0,1,1]
	v_pk_fma_f32 v[12:13], v[4:5], v[12:13], v[22:23] op_sel_hi:[0,1,1]
	v_mul_f32_e32 v21, v20, v14
	v_mul_f32_e32 v22, v20, v15
	v_cvt_pk_bf16_f32 v22, v21, v22
	v_mul_f32_e32 v21, v20, v12
	v_mul_f32_e32 v20, v20, v13
	v_cvt_pk_bf16_f32 v23, v21, v20
	v_lshl_add_u64 v[20:21], s[14:15], 0, v[10:11]
	v_lshl_add_u64 v[10:11], s[12:13], 0, v[10:11]
	s_nop 0
	global_store_dwordx2 v[20:21], v[22:23], off
	s_waitcnt vmcnt(7)
	v_lshlrev_b32_e32 v20, 16, v226
	v_and_b32_e32 v21, 0xffff0000, v226
	v_lshlrev_b32_e32 v10, 16, v227
	v_and_b32_e32 v11, 0xffff0000, v227
	v_pk_mul_f32 v[20:21], v[6:7], v[20:21] op_sel_hi:[0,1]
	v_pk_mul_f32 v[10:11], v[6:7], v[10:11] op_sel_hi:[0,1]
	v_pk_fma_f32 v[10:11], v[4:5], v[12:13], v[10:11] op_sel_hi:[0,1,1]
	v_pk_fma_f32 v[12:13], v[4:5], v[14:15], v[20:21] op_sel_hi:[0,1,1]
	v_lshl_add_u64 v[14:15], v[0:1], 2, s[10:11]
	v_lshlrev_b64 v[20:21], 19, v[2:3]
	v_lshl_add_u64 v[14:15], v[14:15], 0, v[20:21]
	v_lshl_add_u64 v[8:9], v[14:15], 0, v[8:9]
	global_store_dword v[8:9], v12, off
	global_store_dword v[8:9], v13, off offset:2048
	v_add_co_u32_e32 v8, vcc, 0x1000, v8
	s_nop 1
	v_addc_co_u32_e32 v9, vcc, 0, v9, vcc
	global_store_dword v[8:9], v10, off
	global_store_dword v[8:9], v11, off offset:2048
	s_branch .LBB0_787
